# v4: gla_prep triangular 0/1 bf16 operands generated by 64-bit shifts instead of ~550 cmp/cndmask slots per item (G1+G3)
# speedup vs baseline: 1.0298x; 1.0193x over previous
; #define LAS __attribute__((address_space(3)))
; __device__ __forceinline__ unsigned pk_bf16(float lo, float hi) { unsigned r; asm volatile("v_cvt_pk_bf16_f32 %0, %1, %2" : "=v"(r) : "v"(lo), "v"(hi)); return r; }
; __device__ __forceinline__ f32x4 mfma16(bf16x8 a, bf16x8 b, f32x4 c) { return __builtin_amdgcn_mfma_f32_16x16x32_bf16(a, b, c, 0, 0, 0); }
; __device__ __forceinline__ void gla_prep(const PrepRegs& R, LAS unsigned char* lds, int wave, int fr, int fq) {
;     ...
;     for (int q = 0; q < 3; ++q) { const int tile = wave * 3 + q, mi = tile / 6, ni = tile % 6, dir = ni / 3, c = (ni % 3) * 16 + fr;
;         const f32x4 acc = mfma16(as_bf8(R.ga[q]), as_bf8(R.bw[q]), (f32x4){0.f, 0.f, 0.f, 0.f});
;         float g[4];
; #pragma unroll
;         for (int i = 0; i < 4; ++i) { const float sv = acc[i] + R.bias[q]; g[i] = (fminf(sv, 0.f) - __logf(1.f + __expf(-fabsf(sv)))) * (1.0f / 16.0f); }
;         u32x2 w2; w2.x = pk_bf16(g[0], g[1]); w2.y = pk_bf16(g[2], g[3]);
;         *(LAS u32x2*)(lds + GL_GT + (dir * 48 + c) * 144 + (mi * 16 + fq * 4) * 2) = w2; }
.LBB0_698:
	s_or_b64 exec, exec, s[4:5]
	s_waitcnt vmcnt(1)
	v_cvt_pk_bf16_f32 v30, v113, v112
	v_cvt_pk_bf16_f32 v31, v115, v114
	v_cvt_pk_bf16_f32 v32, v117, v116
	v_cvt_pk_bf16_f32 v33, v119, v118
	v_and_b32_e32 v30, v140, v30
	v_and_b32_e32 v31, v140, v31
	v_and_b32_e32 v32, v140, v32
	v_and_b32_e32 v33, v140, v33
	v_cvt_pk_bf16_f32 v34, v121, v120
	v_cvt_pk_bf16_f32 v35, v123, v122
	v_cvt_pk_bf16_f32 v36, v125, v124
	v_cvt_pk_bf16_f32 v37, v127, v126
	v_and_b32_e32 v34, v141, v34
	v_and_b32_e32 v35, v141, v35
	v_and_b32_e32 v36, v141, v36
	v_and_b32_e32 v37, v141, v37
	v_cvt_pk_bf16_f32 v38, v133, v132
	v_cvt_pk_bf16_f32 v39, v135, v134
	v_cvt_pk_bf16_f32 v40, v137, v136
	v_cvt_pk_bf16_f32 v41, v139, v138
	v_and_b32_e32 v38, v142, v38
	v_and_b32_e32 v39, v142, v39
	v_and_b32_e32 v40, v142, v40
	v_and_b32_e32 v41, v142, v41
	v_mfma_f32_16x16x32_bf16 v[18:21], v[18:21], v[30:33], 0
	s_barrier
	v_or_b32_e32 v33, 2, v61
	v_or_b32_e32 v47, 34, v61
	s_waitcnt vmcnt(4)
	s_nop 3
	v_add_f32_e32 v18, v78, v18
	v_mul_f32_e64 v30, |v18|, s33
	v_exp_f32_e32 v30, v30
	v_add_f32_e32 v19, v78, v19
	v_min_f32_e32 v18, 0, v18
	v_add_f32_e32 v20, v78, v20
	v_add_f32_e32 v30, 1.0, v30
	v_cmp_gt_f32_e64 s[18:19], s68, v30
	v_add_f32_e32 v21, v78, v21
	v_or_b32_e32 v58, 37, v61
	v_cndmask_b32_e64 v31, 0, 32, s[18:19]
	v_ldexp_f32 v30, v30, v31
	v_log_f32_e32 v30, v30
	v_mul_f32_e64 v31, |v19|, s33
	v_exp_f32_e32 v31, v31
	v_min_f32_e32 v19, 0, v19
	v_mul_f32_e32 v32, 0x3f317217, v30
	v_fma_f32 v32, v30, s2, -v32
	v_fmac_f32_e32 v32, 0x3377d1cf, v30
	v_fmac_f32_e32 v32, 0x3f317217, v30
	v_cmp_lt_f32_e64 s[20:21], |v30|, s83
	v_add_f32_e32 v31, 1.0, v31
	s_nop 0
	v_cndmask_b32_e64 v30, v30, v32, s[20:21]
	v_cndmask_b32_e64 v32, 0, v241, s[18:19]
	v_cmp_gt_f32_e64 s[18:19], s68, v31
	v_sub_f32_e32 v30, v30, v32
	v_sub_f32_e32 v18, v18, v30
	v_cndmask_b32_e64 v32, 0, 32, s[18:19]
	v_ldexp_f32 v31, v31, v32
	v_log_f32_e32 v31, v31
	v_mul_f32_e64 v32, |v20|, s33
	v_exp_f32_e32 v32, v32
	v_min_f32_e32 v20, 0, v20
	v_mul_f32_e32 v30, 0x3f317217, v31
	v_fma_f32 v30, v31, s2, -v30
	v_fmac_f32_e32 v30, 0x3377d1cf, v31
	v_fmac_f32_e32 v30, 0x3f317217, v31
	v_cmp_lt_f32_e64 s[20:21], |v31|, s83
	v_mul_f32_e32 v18, 0x3d800000, v18
	s_nop 0
	v_cndmask_b32_e64 v30, v31, v30, s[20:21]
	v_cndmask_b32_e64 v31, 0, v241, s[18:19]
	v_sub_f32_e32 v30, v30, v31
	v_add_f32_e32 v31, 1.0, v32
	v_cmp_gt_f32_e64 s[18:19], s68, v31
	v_sub_f32_e32 v19, v19, v30
	v_mul_f32_e32 v19, 0x3d800000, v19
	v_cndmask_b32_e64 v32, 0, 32, s[18:19]
	v_ldexp_f32 v31, v31, v32
	v_log_f32_e32 v31, v31
	v_mul_f32_e64 v32, |v21|, s33
	v_exp_f32_e32 v32, v32
	v_min_f32_e32 v21, 0, v21
	v_mul_f32_e32 v30, 0x3f317217, v31
	v_fma_f32 v30, v31, s2, -v30
	v_fmac_f32_e32 v30, 0x3377d1cf, v31
	v_fmac_f32_e32 v30, 0x3f317217, v31
	v_cmp_lt_f32_e64 s[20:21], |v31|, s83
	s_nop 1
	v_cndmask_b32_e64 v30, v31, v30, s[20:21]
	v_cndmask_b32_e64 v31, 0, v241, s[18:19]
	v_sub_f32_e32 v30, v30, v31
	v_add_f32_e32 v31, 1.0, v32
	v_cmp_gt_f32_e64 s[18:19], s68, v31
	v_sub_f32_e32 v20, v20, v30
	v_mul_f32_e32 v20, 0x3d800000, v20
	v_cndmask_b32_e64 v32, 0, 32, s[18:19]
	v_ldexp_f32 v31, v31, v32
	v_log_f32_e32 v31, v31
	v_mad_i32_i24 v32, v70, 48, v52
	v_or_b32_e32 v52, 35, v61
	v_mul_f32_e32 v30, 0x3f317217, v31
	v_fma_f32 v30, v31, s2, -v30
	v_fmac_f32_e32 v30, 0x3377d1cf, v31
	v_fmac_f32_e32 v30, 0x3f317217, v31
	v_cmp_lt_f32_e64 s[20:21], |v31|, s83
	s_nop 1
	v_cndmask_b32_e64 v30, v31, v30, s[20:21]
	v_cndmask_b32_e64 v31, 0, v241, s[18:19]
	v_sub_f32_e32 v30, v30, v31
	v_sub_f32_e32 v21, v21, v30
	v_mul_f32_e32 v21, 0x3d800000, v21
	v_cvt_pk_bf16_f32 v30, v18, v19
	v_cvt_pk_bf16_f32 v31, v20, v21
	s_waitcnt vmcnt(3)
	v_mfma_f32_16x16x32_bf16 v[18:21], v[22:25], v[34:37], 0
	v_mul_lo_u32 v23, v32, s55
	v_add_u32_e32 v23, 0, v23
	v_lshlrev_b32_e32 v24, 5, v75
	v_add3_u32 v23, v23, v24, v61
	ds_write_b64 v23, v[30:31]
	s_waitcnt vmcnt(2)
	s_nop 1
	v_add_f32_e32 v18, v79, v18
	v_mul_f32_e64 v22, |v18|, s33
	v_exp_f32_e32 v22, v22
	v_add_f32_e32 v19, v79, v19
	v_mul_f32_e64 v24, |v19|, s33
	v_exp_f32_e32 v24, v24
	v_add_f32_e32 v22, 1.0, v22
	v_cmp_gt_f32_e64 s[18:19], s68, v22
	v_min_f32_e32 v18, 0, v18
	v_add_f32_e32 v20, v79, v20
	v_cndmask_b32_e64 v25, 0, 32, s[18:19]
	v_ldexp_f32 v22, v22, v25
	v_log_f32_e32 v22, v22
	v_min_f32_e32 v19, 0, v19
	v_add_f32_e32 v21, v79, v21
	v_or_b32_e32 v32, 1, v61
	v_mul_f32_e32 v23, 0x3f317217, v22
	v_fma_f32 v23, v22, s2, -v23
	v_fmac_f32_e32 v23, 0x3377d1cf, v22
	v_fmac_f32_e32 v23, 0x3f317217, v22
	v_cmp_lt_f32_e64 s[20:21], |v22|, s83
	v_or_b32_e32 v34, 3, v61
	v_or_b32_e32 v35, 4, v61
	v_cndmask_b32_e64 v22, v22, v23, s[20:21]
	v_cndmask_b32_e64 v23, 0, v241, s[18:19]
	v_sub_f32_e32 v22, v22, v23
	v_add_f32_e32 v23, 1.0, v24
	v_cmp_gt_f32_e64 s[18:19], s68, v23
	v_sub_f32_e32 v18, v18, v22
	v_mul_f32_e32 v18, 0x3d800000, v18
	v_cndmask_b32_e64 v24, 0, 32, s[18:19]
	v_ldexp_f32 v23, v23, v24
	v_log_f32_e32 v23, v23
	v_mul_f32_e64 v24, |v20|, s33
	v_exp_f32_e32 v24, v24
	v_min_f32_e32 v20, 0, v20
	v_mul_f32_e32 v22, 0x3f317217, v23
	v_fma_f32 v22, v23, s2, -v22
	v_fmac_f32_e32 v22, 0x3377d1cf, v23
	v_fmac_f32_e32 v22, 0x3f317217, v23
	v_cmp_lt_f32_e64 s[20:21], |v23|, s83
	v_or_b32_e32 v36, 5, v61
	v_or_b32_e32 v37, 6, v61
	v_cndmask_b32_e64 v22, v23, v22, s[20:21]
	v_cndmask_b32_e64 v23, 0, v241, s[18:19]
	v_sub_f32_e32 v22, v22, v23
	v_add_f32_e32 v23, 1.0, v24
	v_cmp_gt_f32_e64 s[18:19], s68, v23
	v_sub_f32_e32 v19, v19, v22
	v_mul_f32_e32 v19, 0x3d800000, v19
	v_cndmask_b32_e64 v24, 0, 32, s[18:19]
	v_ldexp_f32 v23, v23, v24
	v_log_f32_e32 v23, v23
	v_mul_f32_e64 v24, |v21|, s33
	v_exp_f32_e32 v24, v24
	v_min_f32_e32 v21, 0, v21
	v_mul_f32_e32 v22, 0x3f317217, v23
	v_fma_f32 v22, v23, s2, -v22
	v_fmac_f32_e32 v22, 0x3377d1cf, v23
	v_fmac_f32_e32 v22, 0x3f317217, v23
	v_cmp_lt_f32_e64 s[20:21], |v23|, s83
	s_nop 1
	v_cndmask_b32_e64 v22, v23, v22, s[20:21]
	v_cndmask_b32_e64 v23, 0, v241, s[18:19]
	v_sub_f32_e32 v22, v22, v23
	v_add_f32_e32 v23, 1.0, v24
	v_cmp_gt_f32_e64 s[18:19], s68, v23
	v_sub_f32_e32 v20, v20, v22
	v_mul_f32_e32 v20, 0x3d800000, v20
	v_cndmask_b32_e64 v24, 0, 32, s[18:19]
	v_ldexp_f32 v23, v23, v24
	v_log_f32_e32 v23, v23
	v_mad_i32_i24 v24, v66, 48, v54
	v_mul_lo_u32 v24, v24, s55
	v_add_u32_e32 v24, 0, v24
	v_mul_f32_e32 v22, 0x3f317217, v23
	v_fma_f32 v22, v23, s2, -v22
	v_fmac_f32_e32 v22, 0x3377d1cf, v23
	v_fmac_f32_e32 v22, 0x3f317217, v23
	v_cmp_lt_f32_e64 s[20:21], |v23|, s83
	s_nop 1
	v_cndmask_b32_e64 v22, v23, v22, s[20:21]
	v_cndmask_b32_e64 v23, 0, v241, s[18:19]
	v_sub_f32_e32 v22, v22, v23
	v_sub_f32_e32 v21, v21, v22
	v_mul_f32_e32 v21, 0x3d800000, v21
	v_cvt_pk_bf16_f32 v22, v18, v19
	v_cvt_pk_bf16_f32 v23, v20, v21
	s_waitcnt vmcnt(1)
; #define LAS __attribute__((address_space(3)))
; __device__ __forceinline__ unsigned pk_bf16(float lo, float hi) { unsigned r; asm volatile("v_cvt_pk_bf16_f32 %0, %1, %2" : "=v"(r) : "v"(lo), "v"(hi)); return r; }
; __device__ __forceinline__ f32x4 mfma16(bf16x8 a, bf16x8 b, f32x4 c) { return __builtin_amdgcn_mfma_f32_16x16x32_bf16(a, b, c, 0, 0, 0); }
; __device__ __forceinline__ void gla_prep(const PrepRegs& R, LAS unsigned char* lds, int wave, int fr, int fq) {
;     ...
; #pragma unroll
;         for (int i = 0; i < 4; ++i) { const float sv = acc[i] + R.bias[q]; g[i] = (fminf(sv, 0.f) - __logf(1.f + __expf(-fabsf(sv)))) * (1.0f / 16.0f); }
;         u32x2 w2; w2.x = pk_bf16(g[0], g[1]); w2.y = pk_bf16(g[2], g[3]);
;         *(LAS u32x2*)(lds + GL_GT + (dir * 48 + c) * 144 + (mi * 16 + fq * 4) * 2) = w2; }
;     __syncthreads();
; #pragma unroll
;     for (int q = 0; q < 3; ++q) { const int tile = wave * 3 + q, mi = tile / 6, ni = tile % 6, dir = ni / 3;
;         f32x4 acc = (f32x4){0.f, 0.f, 0.f, 0.f};
; #pragma unroll
;         for (int kk = 0; kk < 2; ++kk) { const int t = mi * 16 + fr; bf16x8 tri;
; #pragma unroll
;             for (int e = 0; e < 8; ++e) { const int sidx = kk * 32 + fq * 8 + e; tri[e] = (dir ? (sidx >= t) : (sidx <= t)) ? (short)0x3F80 : (short)0; }
;             const bf16x8 bb = *(const LAS bf16x8*)(lds + GL_GT + (ni * 16 + fr) * 144 + kk * 64 + fq * 16);
;             acc = mfma16(tri, bb, acc); }
	v_mfma_f32_16x16x32_bf16 v[18:21], v[26:29], v[38:41], 0
	v_lshlrev_b32_e32 v26, 5, v76
	v_add3_u32 v24, v24, v26, v61
	ds_write_b64 v24, v[22:23]
	v_or_b32_e32 v38, 7, v61
	v_or_b32_e32 v39, 32, v61
	s_waitcnt vmcnt(0)
	s_nop 1
	v_add_f32_e32 v18, v80, v18
	v_mul_f32_e64 v25, |v18|, s33
	v_exp_f32_e32 v25, v25
	v_add_f32_e32 v19, v80, v19
	v_mul_f32_e64 v23, |v19|, s33
	v_exp_f32_e32 v23, v23
	v_add_f32_e32 v25, 1.0, v25
	v_cmp_gt_f32_e64 s[18:19], s68, v25
	v_min_f32_e32 v18, 0, v18
	v_add_f32_e32 v23, 1.0, v23
	v_cndmask_b32_e64 v27, 0, 32, s[18:19]
	v_ldexp_f32 v25, v25, v27
	v_log_f32_e32 v25, v25
	v_cndmask_b32_e64 v24, 0, v241, s[18:19]
	v_cmp_gt_f32_e64 s[18:19], s68, v23
	v_add_f32_e32 v20, v80, v20
	v_mul_f32_e32 v22, 0x3f317217, v25
	v_fma_f32 v22, v25, s2, -v22
	v_fmac_f32_e32 v22, 0x3377d1cf, v25
	v_fmac_f32_e32 v22, 0x3f317217, v25
	v_cmp_lt_f32_e64 s[20:21], |v25|, s83
	v_min_f32_e32 v19, 0, v19
	v_add_f32_e32 v21, v80, v21
	v_cndmask_b32_e64 v22, v25, v22, s[20:21]
	v_sub_f32_e32 v22, v22, v24
	v_cndmask_b32_e64 v24, 0, 32, s[18:19]
	v_ldexp_f32 v23, v23, v24
	v_log_f32_e32 v23, v23
	v_sub_f32_e32 v18, v18, v22
	v_mul_f32_e64 v24, |v20|, s33
	v_exp_f32_e32 v24, v24
	v_mul_f32_e32 v22, 0x3f317217, v23
	v_fma_f32 v22, v23, s2, -v22
	v_fmac_f32_e32 v22, 0x3377d1cf, v23
	v_fmac_f32_e32 v22, 0x3f317217, v23
	v_cmp_lt_f32_e64 s[20:21], |v23|, s83
	v_min_f32_e32 v20, 0, v20
	v_mul_f32_e32 v18, 0x3d800000, v18
	v_cndmask_b32_e64 v22, v23, v22, s[20:21]
	v_cndmask_b32_e64 v23, 0, v241, s[18:19]
	v_sub_f32_e32 v22, v22, v23
	v_add_f32_e32 v23, 1.0, v24
	v_cmp_gt_f32_e64 s[18:19], s68, v23
	v_sub_f32_e32 v19, v19, v22
	v_mul_f32_e32 v19, 0x3d800000, v19
	v_cndmask_b32_e64 v24, 0, 32, s[18:19]
	v_ldexp_f32 v23, v23, v24
	v_log_f32_e32 v23, v23
	v_mul_f32_e64 v24, |v21|, s33
	v_exp_f32_e32 v24, v24
	v_min_f32_e32 v21, 0, v21
	v_mul_f32_e32 v22, 0x3f317217, v23
	v_fma_f32 v22, v23, s2, -v22
	v_fmac_f32_e32 v22, 0x3377d1cf, v23
	v_fmac_f32_e32 v22, 0x3f317217, v23
	v_cmp_lt_f32_e64 s[20:21], |v23|, s83
	v_cvt_pk_bf16_f32 v18, v18, v19
	v_or_b32_e32 v40, 33, v61
	s_nop 0
	v_cndmask_b32_e64 v22, v23, v22, s[20:21]
	v_cndmask_b32_e64 v23, 0, v241, s[18:19]
	v_sub_f32_e32 v22, v22, v23
	v_add_f32_e32 v23, 1.0, v24
	v_cmp_gt_f32_e64 s[18:19], s68, v23
	v_sub_f32_e32 v20, v20, v22
	v_mul_f32_e32 v20, 0x3d800000, v20
	v_cndmask_b32_e64 v24, 0, 32, s[18:19]
	v_ldexp_f32 v23, v23, v24
	v_log_f32_e32 v23, v23
	s_nop 0
	v_mul_f32_e32 v22, 0x3f317217, v23
	v_fma_f32 v22, v23, s2, -v22
	v_fmac_f32_e32 v22, 0x3377d1cf, v23
	v_fmac_f32_e32 v22, 0x3f317217, v23
	v_cmp_lt_f32_e64 s[20:21], |v23|, s83
	s_nop 1
	v_cndmask_b32_e64 v22, v23, v22, s[20:21]
	v_cndmask_b32_e64 v23, 0, v241, s[18:19]
	v_sub_f32_e32 v22, v22, v23
	v_sub_f32_e32 v21, v21, v22
	v_mul_f32_e32 v21, 0x3d800000, v21
	v_cvt_pk_bf16_f32 v19, v20, v21
	v_mad_i32_i24 v20, v63, 48, v56
	v_mul_lo_u32 v20, v20, s55
	v_add_u32_e32 v20, 0, v20
	v_lshlrev_b32_e32 v21, 5, v77
	v_add3_u32 v20, v20, v21, v61
	ds_write_b64 v20, v[18:19]
	v_or_b32_e32 v19, v69, v43
	v_add_u32_e32 v18, 0, v0
	v_lshl_or_b32 v21, v74, 4, v43
	v_cmp_le_i32_e64 s[18:19], v61, v19
	v_add_u32_e32 v20, 2, v74
	v_mad_i32_i24 v28, v21, s55, v18
	v_cndmask_b32_e64 v21, 0, 1, s[18:19]
	v_cmp_ge_i32_e64 s[18:19], v61, v19
	s_waitcnt lgkmcnt(0)
	s_barrier
	s_lshr_b32 s100, s89, 7
	s_lshl_b32 s100, s100, 4
	v_add_u32_e32 v160, s100, v43
	v_sub_u32_e32 v160, v160, v61
	v_subrev_u32_e32 v161, 32, v160
	v_lshlrev_b32_e32 v160, 4, v160
	v_lshlrev_b32_e32 v161, 4, v161
	v_mov_b32_e32 v166, 0x3f803f80
	v_mov_b32_e32 v167, 0
	s_bitcmp1_b32 s89, 6
	s_cbranch_scc1 .Ltri_dir1_g1
	v_sub_u32_e32 v162, 16, v160
	v_med3_i32 v162, v162, 0, 32
	v_lshrrev_b64 v[164:165], v162, v[166:167]
	v_mov_b32_e32 v152, v164
	v_sub_u32_e32 v162, 48, v160
	v_med3_i32 v162, v162, 0, 32
	v_lshrrev_b64 v[164:165], v162, v[166:167]
	v_mov_b32_e32 v153, v164
	v_sub_u32_e32 v162, 0x50, v160
	v_med3_i32 v162, v162, 0, 32
	v_lshrrev_b64 v[164:165], v162, v[166:167]
	v_mov_b32_e32 v154, v164
	v_sub_u32_e32 v162, 0x70, v160
	v_med3_i32 v162, v162, 0, 32
	v_lshrrev_b64 v[164:165], v162, v[166:167]
	v_mov_b32_e32 v155, v164
	v_sub_u32_e32 v162, 16, v161
	v_med3_i32 v162, v162, 0, 32
	v_lshrrev_b64 v[164:165], v162, v[166:167]
	v_mov_b32_e32 v156, v164
	v_sub_u32_e32 v162, 48, v161
	v_med3_i32 v162, v162, 0, 32
	v_lshrrev_b64 v[164:165], v162, v[166:167]
	v_mov_b32_e32 v157, v164
	v_sub_u32_e32 v162, 0x50, v161
	v_med3_i32 v162, v162, 0, 32
	v_lshrrev_b64 v[164:165], v162, v[166:167]
	v_mov_b32_e32 v158, v164
	v_sub_u32_e32 v162, 0x70, v161
	v_med3_i32 v162, v162, 0, 32
	v_lshrrev_b64 v[164:165], v162, v[166:167]
	v_mov_b32_e32 v159, v164
	s_branch .Ltri_done_g1
.Ltri_dir1_g1:
	v_mov_b32_e32 v162, v160
	v_med3_i32 v162, v162, 0, 32
	v_lshlrev_b64 v[164:165], v162, v[166:167]
	v_mov_b32_e32 v152, v164
	v_subrev_u32_e32 v162, 32, v160
	v_med3_i32 v162, v162, 0, 32
	v_lshlrev_b64 v[164:165], v162, v[166:167]
	v_mov_b32_e32 v153, v164
	v_subrev_u32_e32 v162, 64, v160
	v_med3_i32 v162, v162, 0, 32
	v_lshlrev_b64 v[164:165], v162, v[166:167]
	v_mov_b32_e32 v154, v164
	v_subrev_u32_e32 v162, 0x60, v160
	v_med3_i32 v162, v162, 0, 32
	v_lshlrev_b64 v[164:165], v162, v[166:167]
	v_mov_b32_e32 v155, v164
	v_mov_b32_e32 v162, v161
	v_med3_i32 v162, v162, 0, 32
	v_lshlrev_b64 v[164:165], v162, v[166:167]
	v_mov_b32_e32 v156, v164
	v_subrev_u32_e32 v162, 32, v161
	v_med3_i32 v162, v162, 0, 32
	v_lshlrev_b64 v[164:165], v162, v[166:167]
	v_mov_b32_e32 v157, v164
	v_subrev_u32_e32 v162, 64, v161
	v_med3_i32 v162, v162, 0, 32
	v_lshlrev_b64 v[164:165], v162, v[166:167]
	v_mov_b32_e32 v158, v164
	v_subrev_u32_e32 v162, 0x60, v161
	v_med3_i32 v162, v162, 0, 32
	v_lshlrev_b64 v[164:165], v162, v[166:167]
	v_mov_b32_e32 v159, v164
; #define LAS __attribute__((address_space(3)))
; __device__ __forceinline__ f32x4 mfma16(bf16x8 a, bf16x8 b, f32x4 c) { return __builtin_amdgcn_mfma_f32_16x16x32_bf16(a, b, c, 0, 0, 0); }
; __device__ __forceinline__ void gla_prep(const PrepRegs& R, LAS unsigned char* lds, int wave, int fr, int fq) {
;     ...
; #pragma unroll
;     for (int q = 0; q < 3; ++q) { const int tile = wave * 3 + q, mi = tile / 6, ni = tile % 6, dir = ni / 3;
;         f32x4 acc = (f32x4){0.f, 0.f, 0.f, 0.f};
; #pragma unroll
;         for (int kk = 0; kk < 2; ++kk) { const int t = mi * 16 + fr; bf16x8 tri;
; #pragma unroll
;             for (int e = 0; e < 8; ++e) { const int sidx = kk * 32 + fq * 8 + e; tri[e] = (dir ? (sidx >= t) : (sidx <= t)) ? (short)0x3F80 : (short)0; }
;             const bf16x8 bb = *(const LAS bf16x8*)(lds + GL_GT + (ni * 16 + fr) * 144 + kk * 64 + fq * 16);
;             acc = mfma16(tri, bb, acc); }
; #pragma unroll
;         for (int i = 0; i < 4; ++i) G[(dir * 64 + mi * 16 + fq * 4 + i) * 48 + (ni % 3) * 16 + fr] = acc[i]; }
;     __syncthreads();
.Ltri_done_g1:
	v_cndmask_b32_e64 v22, 0, 1, s[18:19]
	v_cmp_gt_u32_e64 s[18:19], 5, v20
	v_or_b32_e32 v56, 36, v61
	v_or_b32_e32 v74, 38, v61
	ds_read_b128 v[24:27], v28
	ds_read_b128 v[28:31], v28 offset:64
	s_waitcnt lgkmcnt(1)
	v_mfma_f32_16x16x32_bf16 v[20:23], v[152:155], v[24:27], 0
	v_lshl_add_u32 v41, v43, 2, 0
	v_or_b32_e32 v54, v65, v43
	v_or_b32_e32 v75, 39, v61
	v_lshlrev_b32_e32 v19, 2, v68
	s_waitcnt lgkmcnt(0)
	v_mfma_f32_16x16x32_bf16 v[20:23], v[156:159], v[28:31], v[20:23]
	v_lshl_add_u32 v24, v70, 6, v69
	v_or_b32_e32 v24, v24, v19
	v_lshlrev_b32_e32 v25, 6, v71
	v_mul_lo_u32 v24, v24, s69
	v_add3_u32 v24, v41, v25, v24
	v_add_u32_e32 v25, 0x3400, v24
	s_nop 7
	ds_write2_b32 v25, v20, v21 offset0:128 offset1:176
	v_add_u32_e32 v20, 0x3600, v24
	v_lshl_or_b32 v21, v73, 4, v43
	ds_write2_b32 v20, v22, v23 offset0:96 offset1:144
	v_add_u32_e32 v20, 2, v73
	v_mad_u64_u32 v[28:29], s[4:5], v21, s55, v[18:19]
	v_cmp_gt_u32_e64 s[18:19], 5, v20
	ds_read_b128 v[24:27], v28
	ds_read_b128 v[28:31], v28 offset:64
	s_waitcnt lgkmcnt(1)
	v_mfma_f32_16x16x32_bf16 v[20:23], v[152:155], v[24:27], 0
	v_or_b32_e32 v54, v62, v43
	s_waitcnt lgkmcnt(0)
	v_mfma_f32_16x16x32_bf16 v[20:23], v[156:159], v[28:31], v[20:23]
	v_lshl_add_u32 v24, v66, 6, v65
	v_or_b32_e32 v24, v24, v19
	v_lshlrev_b32_e32 v25, 6, v67
	v_mul_lo_u32 v24, v24, s69
	v_add3_u32 v24, v41, v25, v24
	v_add_u32_e32 v25, 0x3400, v24
	s_nop 7
	ds_write2_b32 v25, v20, v21 offset0:128 offset1:176
	v_add_u32_e32 v20, 0x3600, v24
	v_lshl_or_b32 v21, v72, 4, v43
	ds_write2_b32 v20, v22, v23 offset0:96 offset1:144
	v_add_u32_e32 v20, 2, v72
	v_mad_u64_u32 v[28:29], s[4:5], v21, s55, v[18:19]
	v_cmp_gt_u32_e64 s[18:19], 5, v20
	ds_read_b128 v[24:27], v28
	ds_read_b128 v[28:31], v28 offset:64
	s_waitcnt lgkmcnt(1)
	v_mfma_f32_16x16x32_bf16 v[20:23], v[152:155], v[24:27], 0
	v_lshl_add_u32 v18, v63, 6, v62
	v_or_b32_e32 v18, v18, v19
	v_mul_lo_u32 v18, v18, s69
	s_waitcnt lgkmcnt(0)
	v_mfma_f32_16x16x32_bf16 v[20:23], v[156:159], v[28:31], v[20:23]
	v_lshlrev_b32_e32 v24, 6, v64
	v_add3_u32 v18, v41, v24, v18
	v_add_u32_e32 v24, 0x3400, v18
	v_add_u32_e32 v18, 0x3600, v18
	s_nop 7
	ds_write2_b32 v24, v20, v21 offset0:128 offset1:176
	ds_write2_b32 v18, v22, v23 offset0:96 offset1:144
	s_waitcnt lgkmcnt(0)
	s_barrier
	s_and_saveexec_b64 s[18:19], s[16:17]
	s_cbranch_execz .LBB0_828
; #define LAS __attribute__((address_space(3)))
; __device__ __forceinline__ bf16_t f2bf(float f) { unsigned u = __float_as_uint(f); u += 0x7FFFu + ((u >> 16) & 1u); return (bf16_t)(u >> 16); }
; __device__ __forceinline__ float bflo(unsigned w) { return __uint_as_float(w << 16); }
; __device__ __forceinline__ float bfhi(unsigned w) { return __uint_as_float(w & 0xffff0000u); }
; __device__ __forceinline__ void gla_g1_item(int wv, const Params& p, int l, int it, LAS unsigned char* lds) {
;     ...
;     if (tid < 384) { const int t = t3;
;         float x1[4] = {bflo(w1.x), bfhi(w1.x), bflo(w1.y), bfhi(w1.y)}, x2[4] = {bflo(w2.x), bfhi(w2.x), bflo(w2.y), bfhi(w2.y)};
;         { const float cn[4] = {ra[0], ra[2], rb[0], rb[2]}, sn[4] = {ra[1], ra[3], rb[1], rb[3]};
; #pragma unroll
;             for (int e = 0; e < 4; ++e) { const float a1 = x1[e], a2 = x2[e]; x1[e] = a1 * cn[e] - a2 * sn[e]; x2[e] = a2 * cn[e] + a1 * sn[e]; } }
; #pragma unroll
;         for (int dir = 0; dir < 2; ++dir) { const int tl = dir ? 0 : 63;
;             const f32x4 b1 = *(const LAS f32x4*)(G + (dir * 64 + t) * 48 + c1), b2 = *(const LAS f32x4*)(G + (dir * 64 + t) * 48 + c1 + 12);
;             const f32x4 l1 = *(const LAS f32x4*)(G + (dir * 64 + tl) * 48 + c1), l2 = *(const LAS f32x4*)(G + (dir * 64 + tl) * 48 + c1 + 12);
; #pragma unroll
;             for (int e = 0; e < 4; ++e) {
;                 *(LAS bf16_t*)(lds + GL_X + (dir * 48 + c1 + e) * 144 + t * 2) = f2bf(x1[e] * __expf(l1[e] - b1[e]));
;                 *(LAS bf16_t*)(lds + GL_X + (dir * 48 + c1 + 12 + e) * 144 + t * 2) = f2bf(x2[e] * __expf(l2[e] - b2[e])); } } }
	v_lshlrev_b32_e32 v18, 16, v50
	v_lshlrev_b32_e32 v22, 16, v48
	v_and_b32_e32 v23, 0xffff0000, v48
	v_mul_f32_e32 v27, v15, v22
	v_mul_f32_e32 v31, v15, v18
	v_and_b32_e32 v20, 0xffff0000, v50
	v_lshlrev_b32_e32 v25, 16, v49
	v_fma_f32 v30, v14, v18, -v27
	v_fmac_f32_e32 v31, v14, v22
	v_mul_f32_e32 v14, v17, v23
	v_lshl_add_u32 v18, v46, 2, 0
	v_lshlrev_b32_e32 v21, 16, v51
	v_fma_f32 v32, v16, v20, -v14
	v_mul_f32_e32 v33, v17, v20
	v_mul_f32_e32 v14, v11, v25
	v_mad_u64_u32 v[28:29], s[4:5], v57, s69, v[18:19]
	v_fmac_f32_e32 v33, v16, v23
	v_fma_f32 v34, v10, v21, -v14
	v_mul_f32_e32 v35, v11, v21
	ds_read_b128 v[14:17], v28 offset:13824
	ds_read_b128 v[20:23], v18 offset:25920
	v_and_b32_e32 v26, 0xffff0000, v49
	v_and_b32_e32 v24, 0xffff0000, v51
	v_fmac_f32_e32 v35, v10, v25
	v_mul_f32_e32 v10, v13, v26
	v_fma_f32 v29, v12, v24, -v10
	s_waitcnt lgkmcnt(0)
	v_sub_f32_e32 v10, v20, v14
	v_mul_f32_e32 v36, v13, v24
	v_mul_f32_e32 v10, 0x3fb8aa3b, v10
	v_fmac_f32_e32 v36, v12, v26
	v_exp_f32_e32 v14, v10
	ds_read_b128 v[10:13], v28 offset:13872
	ds_read_b128 v[24:27], v18 offset:25968
	v_lshlrev_b32_e32 v37, 1, v57
	s_add_i32 s4, 0, 0x16000
	v_mul_f32_e32 v14, v30, v14
	v_bfe_u32 v20, v14, 16, 1
	s_waitcnt lgkmcnt(0)
	v_sub_f32_e32 v10, v24, v10
	v_add3_u32 v14, v14, v20, s54
	v_mul_f32_e32 v10, 0x3fb8aa3b, v10
	v_mul_i32_i24_e32 v20, 0x90, v46
	v_exp_f32_e32 v10, v10
	v_add3_u32 v37, s4, v37, v20
	ds_write_b16_d16_hi v37, v14
	v_sub_f32_e32 v14, v21, v15
	v_mul_f32_e32 v14, 0x3fb8aa3b, v14
	v_exp_f32_e32 v14, v14
	v_mul_f32_e32 v10, v31, v10
	v_sub_f32_e32 v11, v25, v11
	v_bfe_u32 v15, v10, 16, 1
	v_mul_f32_e32 v11, 0x3fb8aa3b, v11
	v_add3_u32 v10, v10, v15, s54
	v_exp_f32_e32 v11, v11
	ds_write_b16_d16_hi v37, v10 offset:1728
	v_mul_f32_e32 v10, v32, v14
	v_bfe_u32 v14, v10, 16, 1
	v_add3_u32 v10, v10, v14, s54
	ds_write_b16_d16_hi v37, v10 offset:144
	v_mul_f32_e32 v10, v33, v11
	v_sub_f32_e32 v11, v22, v16
	v_mul_f32_e32 v11, 0x3fb8aa3b, v11
	v_exp_f32_e32 v11, v11
	v_bfe_u32 v14, v10, 16, 1
	v_add3_u32 v10, v10, v14, s54
	ds_write_b16_d16_hi v37, v10 offset:1872
	v_mul_f32_e32 v10, v34, v11
	v_sub_f32_e32 v11, v26, v12
	v_mul_f32_e32 v11, 0x3fb8aa3b, v11
	v_exp_f32_e32 v11, v11
	v_bfe_u32 v12, v10, 16, 1
	v_add3_u32 v10, v10, v12, s54
	ds_write_b16_d16_hi v37, v10 offset:288
	v_mul_f32_e32 v10, v35, v11
	v_sub_f32_e32 v11, v23, v17
	v_mul_f32_e32 v11, 0x3fb8aa3b, v11
	v_exp_f32_e32 v11, v11
	v_bfe_u32 v12, v10, 16, 1
	v_add3_u32 v10, v10, v12, s54
	ds_write_b16_d16_hi v37, v10 offset:2016
	v_mul_f32_e32 v10, v29, v11
	v_sub_f32_e32 v11, v27, v13
	v_mul_f32_e32 v11, 0x3fb8aa3b, v11
	v_exp_f32_e32 v11, v11
	v_bfe_u32 v12, v10, 16, 1
	v_add3_u32 v10, v10, v12, s54
	ds_write_b16_d16_hi v37, v10 offset:432
	v_mul_f32_e32 v10, v36, v11
	v_bfe_u32 v11, v10, 16, 1
	v_add3_u32 v10, v10, v11, s54
	ds_write_b16_d16_hi v37, v10 offset:2160
	ds_read_b128 v[10:13], v28 offset:26112
	ds_read_b128 v[14:17], v18 offset:26112
	ds_read_b128 v[20:23], v28 offset:26160
	ds_read_b128 v[24:27], v18 offset:26160
	s_waitcnt lgkmcnt(2)
	v_sub_f32_e32 v10, v14, v10
	v_mul_f32_e32 v10, 0x3fb8aa3b, v10
	v_exp_f32_e32 v10, v10
	s_waitcnt lgkmcnt(0)
	v_sub_f32_e32 v14, v24, v20
	v_mul_f32_e32 v14, 0x3fb8aa3b, v14
	v_exp_f32_e32 v14, v14
	v_mul_f32_e32 v10, v30, v10
	v_sub_f32_e32 v11, v15, v11
	v_bfe_u32 v18, v10, 16, 1
	v_mul_f32_e32 v11, 0x3fb8aa3b, v11
	v_add3_u32 v10, v10, v18, s54
	v_exp_f32_e32 v11, v11
	ds_write_b16_d16_hi v37, v10 offset:6912
	v_mul_f32_e32 v10, v31, v14
	v_bfe_u32 v14, v10, 16, 1
	v_add3_u32 v10, v10, v14, s54
	ds_write_b16_d16_hi v37, v10 offset:8640
	v_mul_f32_e32 v10, v32, v11
	v_sub_f32_e32 v11, v25, v21
	v_mul_f32_e32 v11, 0x3fb8aa3b, v11
	v_exp_f32_e32 v11, v11
	v_bfe_u32 v14, v10, 16, 1
	v_add3_u32 v10, v10, v14, s54
	ds_write_b16_d16_hi v37, v10 offset:7056
	v_mul_f32_e32 v10, v33, v11
	v_sub_f32_e32 v11, v16, v12
	v_mul_f32_e32 v11, 0x3fb8aa3b, v11
	v_exp_f32_e32 v11, v11
	v_bfe_u32 v12, v10, 16, 1
	v_add3_u32 v10, v10, v12, s54
	ds_write_b16_d16_hi v37, v10 offset:8784
	v_mul_f32_e32 v10, v34, v11
	v_sub_f32_e32 v11, v26, v22
	v_mul_f32_e32 v11, 0x3fb8aa3b, v11
	v_exp_f32_e32 v11, v11
	v_bfe_u32 v12, v10, 16, 1
	v_add3_u32 v10, v10, v12, s54
	ds_write_b16_d16_hi v37, v10 offset:7200
	v_mul_f32_e32 v10, v35, v11
	v_sub_f32_e32 v11, v17, v13
	v_mul_f32_e32 v11, 0x3fb8aa3b, v11
	v_exp_f32_e32 v11, v11
	v_bfe_u32 v12, v10, 16, 1
	v_add3_u32 v10, v10, v12, s54
	ds_write_b16_d16_hi v37, v10 offset:8928
	v_mul_f32_e32 v10, v29, v11
	v_sub_f32_e32 v11, v27, v23
	v_mul_f32_e32 v11, 0x3fb8aa3b, v11
	v_exp_f32_e32 v11, v11
	v_bfe_u32 v12, v10, 16, 1
	v_add3_u32 v10, v10, v12, s54
	ds_write_b16_d16_hi v37, v10 offset:7344
	v_mul_f32_e32 v10, v36, v11
	v_bfe_u32 v11, v10, 16, 1
	v_add3_u32 v10, v10, v11, s54
	ds_write_b16_d16_hi v37, v10 offset:9072
	s_or_b64 exec, exec, s[18:19]
	v_add_u32_e32 v10, s87, v44
	s_and_saveexec_b64 s[4:5], vcc
	s_cbranch_execnz .LBB0_829

; #define LAS __attribute__((address_space(3)))
; __device__ __forceinline__ unsigned pk_bf16(float lo, float hi) { unsigned r; asm volatile("v_cvt_pk_bf16_f32 %0, %1, %2" : "=v"(r) : "v"(lo), "v"(hi)); return r; }
; __device__ __forceinline__ f32x4 mfma16(bf16x8 a, bf16x8 b, f32x4 c) { return __builtin_amdgcn_mfma_f32_16x16x32_bf16(a, b, c, 0, 0, 0); }
; __device__ __forceinline__ void gla_prep(const PrepRegs& R, LAS unsigned char* lds, int wave, int fr, int fq) {
;     ...
;     for (int q = 0; q < 3; ++q) { const int tile = wave * 3 + q, mi = tile / 6, ni = tile % 6, dir = ni / 3, c = (ni % 3) * 16 + fr;
;         const f32x4 acc = mfma16(as_bf8(R.ga[q]), as_bf8(R.bw[q]), (f32x4){0.f, 0.f, 0.f, 0.f});
;         float g[4];
; #pragma unroll
;         for (int i = 0; i < 4; ++i) { const float sv = acc[i] + R.bias[q]; g[i] = (fminf(sv, 0.f) - __logf(1.f + __expf(-fabsf(sv)))) * (1.0f / 16.0f); }
;         u32x2 w2; w2.x = pk_bf16(g[0], g[1]); w2.y = pk_bf16(g[2], g[3]);
;         *(LAS u32x2*)(lds + GL_GT + (dir * 48 + c) * 144 + (mi * 16 + fq * 4) * 2) = w2; }
; __device__ __forceinline__ void gla_g3_item(int wv, const Params& p, int l, int b, int n, int h, LAS unsigned char* lds) {
;     ...
;     { const bf16_t* gp = Z + (size_t)(row0 + tf) * ZLD + ZC_GG + h * 96 + part * 12;
; #pragma unroll
;       for (int q4 = 0; q4 < 3; ++q4) ggw[q4] = *(const u32x2*)(gp + q4 * 4); }
.LBB0_991:
	s_or_b64 exec, exec, s[4:5]
	v_and_b32_e32 v59, 7, v83
	v_add_u32_e32 v58, s3, v63
	v_mov_b64_e32 v[60:61], s[36:37]
	v_mad_i64_i32 v[60:61], s[4:5], v58, s86, v[60:61]
	s_lshl_b32 s56, s34, 1
	v_mul_u32_u24_e32 v65, 12, v59
	v_lshl_add_u64 v[106:107], v[60:61], 0, s[56:57]
	v_lshlrev_b32_e32 v60, 1, v65
	v_mov_b32_e32 v61, v1
	v_lshl_add_u64 v[110:111], v[106:107], 0, v[60:61]
	s_waitcnt vmcnt(1)
	v_cvt_pk_bf16_f32 v46, v113, v112
	v_cvt_pk_bf16_f32 v47, v115, v114
	v_cvt_pk_bf16_f32 v48, v117, v116
	v_cvt_pk_bf16_f32 v49, v119, v118
	v_and_b32_e32 v46, v140, v46
	v_and_b32_e32 v47, v140, v47
	v_and_b32_e32 v48, v140, v48
	v_and_b32_e32 v49, v140, v49
	v_cvt_pk_bf16_f32 v50, v121, v120
	v_cvt_pk_bf16_f32 v51, v123, v122
	v_cvt_pk_bf16_f32 v52, v125, v124
	v_cvt_pk_bf16_f32 v53, v127, v126
	v_and_b32_e32 v50, v141, v50
	v_and_b32_e32 v51, v141, v51
	v_and_b32_e32 v52, v141, v52
	v_and_b32_e32 v53, v141, v53
	v_cvt_pk_bf16_f32 v54, v133, v132
	v_cvt_pk_bf16_f32 v55, v135, v134
	v_cvt_pk_bf16_f32 v56, v137, v136
	v_cvt_pk_bf16_f32 v57, v139, v138
	v_and_b32_e32 v54, v142, v54
	v_and_b32_e32 v55, v142, v55
	v_and_b32_e32 v56, v142, v56
	v_and_b32_e32 v57, v142, v57
	v_mfma_f32_16x16x32_bf16 v[106:109], v[6:9], v[46:49], 0
	s_waitcnt vmcnt(3)
	v_mfma_f32_16x16x32_bf16 v[38:41], v[38:41], v[50:53], 0
	v_lshlrev_b32_e32 v52, 5, v100
	s_nop 4
	v_add_f32_e32 v48, v103, v106
	v_mul_f32_e64 v6, |v48|, s33
	v_exp_f32_e32 v49, v6
	v_add_f32_e32 v61, v103, v107
	v_mul_f32_e64 v106, |v61|, s33
	v_exp_f32_e32 v106, v106
	v_add_f32_e32 v49, 1.0, v49
	v_cmp_gt_f32_e64 s[24:25], s68, v49
	v_min_f32_e32 v48, 0, v48
	s_waitcnt vmcnt(2)
	v_add_f32_e32 v38, v104, v38
	v_cndmask_b32_e64 v59, 0, 32, s[24:25]
	v_ldexp_f32 v49, v49, v59
	v_log_f32_e32 v49, v49
	v_mul_f32_e64 v50, |v38|, s33
	v_exp_f32_e32 v50, v50
	global_load_dwordx2 v[46:47], v[110:111], off offset:2320
	global_load_dwordx4 v[6:9], v[110:111], off offset:2304
	v_mul_f32_e32 v59, 0x3f317217, v49
	v_fma_f32 v59, v49, s2, -v59
	v_fmac_f32_e32 v59, 0x3377d1cf, v49
	v_fmac_f32_e32 v59, 0x3f317217, v49
	v_cmp_lt_f32_e64 s[26:27], |v49|, s83
	v_add_f32_e32 v50, 1.0, v50
	s_nop 0
	v_cndmask_b32_e64 v49, v49, v59, s[26:27]
	v_cndmask_b32_e64 v59, 0, v241, s[24:25]
	v_sub_f32_e32 v49, v49, v59
	v_add_f32_e32 v59, 1.0, v106
	v_cmp_gt_f32_e64 s[24:25], s68, v59
	v_sub_f32_e32 v48, v48, v49
	v_min_f32_e32 v49, 0, v61
	v_cndmask_b32_e64 v106, 0, 32, s[24:25]
	v_ldexp_f32 v59, v59, v106
	v_log_f32_e32 v59, v59
	v_add_f32_e32 v106, v103, v108
	v_mul_f32_e64 v107, |v106|, s33
	v_exp_f32_e32 v107, v107
	v_mul_f32_e32 v61, 0x3f317217, v59
	v_fma_f32 v61, v59, s2, -v61
	v_fmac_f32_e32 v61, 0x3377d1cf, v59
	v_fmac_f32_e32 v61, 0x3f317217, v59
	v_cmp_lt_f32_e64 s[26:27], |v59|, s83
	v_add_f32_e32 v103, v103, v109
	v_mul_f32_e32 v48, 0x3d800000, v48
	v_cndmask_b32_e64 v59, v59, v61, s[26:27]
	v_cndmask_b32_e64 v61, 0, v241, s[24:25]
	v_sub_f32_e32 v59, v59, v61
	v_add_f32_e32 v61, 1.0, v107
	v_cmp_gt_f32_e64 s[24:25], s68, v61
	v_sub_f32_e32 v49, v49, v59
	v_min_f32_e32 v59, 0, v106
	v_cndmask_b32_e64 v107, 0, 32, s[24:25]
	v_ldexp_f32 v61, v61, v107
	v_log_f32_e32 v61, v61
	v_mul_f32_e64 v107, |v103|, s33
	v_exp_f32_e32 v107, v107
	v_mul_f32_e32 v49, 0x3d800000, v49
	v_mul_f32_e32 v106, 0x3f317217, v61
	v_fma_f32 v106, v61, s2, -v106
	v_fmac_f32_e32 v106, 0x3377d1cf, v61
	v_fmac_f32_e32 v106, 0x3f317217, v61
	v_cmp_lt_f32_e64 s[26:27], |v61|, s83
	s_barrier
	s_nop 0
	v_cndmask_b32_e64 v61, v61, v106, s[26:27]
	v_cndmask_b32_e64 v106, 0, v241, s[24:25]
	v_sub_f32_e32 v61, v61, v106
	v_add_f32_e32 v106, 1.0, v107
	v_cmp_gt_f32_e64 s[24:25], s68, v106
	v_sub_f32_e32 v59, v59, v61
	v_min_f32_e32 v61, 0, v103
	v_cndmask_b32_e64 v107, 0, 32, s[24:25]
	v_ldexp_f32 v106, v106, v107
	v_log_f32_e32 v106, v106
	v_mul_f32_e32 v59, 0x3d800000, v59
	v_cvt_pk_bf16_f32 v48, v48, v49
	v_add_f32_e32 v39, v104, v39
	v_mul_f32_e32 v103, 0x3f317217, v106
	v_fma_f32 v103, v106, s2, -v103
	v_fmac_f32_e32 v103, 0x3377d1cf, v106
	v_fmac_f32_e32 v103, 0x3f317217, v106
	v_cmp_lt_f32_e64 s[26:27], |v106|, s83
	v_min_f32_e32 v38, 0, v38
	v_add_f32_e32 v40, v104, v40
	v_cndmask_b32_e64 v103, v106, v103, s[26:27]
	v_cndmask_b32_e64 v106, 0, v241, s[24:25]
	v_sub_f32_e32 v103, v103, v106
	v_sub_f32_e32 v61, v61, v103
	v_cmp_gt_f32_e64 s[24:25], s68, v50
	v_mul_f32_e32 v61, 0x3d800000, v61
	v_cvt_pk_bf16_f32 v49, v59, v61
	v_mad_i32_i24 v59, v94, 48, v74
	v_cndmask_b32_e64 v53, 0, 32, s[24:25]
	v_mul_lo_u32 v51, v59, s55
	v_ldexp_f32 v50, v50, v53
	v_add_u32_e32 v51, 0, v51
	v_log_f32_e32 v50, v50
	v_add3_u32 v51, v51, v52, v84
	ds_write_b64 v51, v[48:49]
	v_mul_f32_e64 v49, |v39|, s33
	v_exp_f32_e32 v49, v49
	v_mul_f32_e32 v48, 0x3f317217, v50
	v_fma_f32 v48, v50, s2, -v48
	v_fmac_f32_e32 v48, 0x3377d1cf, v50
	v_fmac_f32_e32 v48, 0x3f317217, v50
	v_cmp_lt_f32_e64 s[26:27], |v50|, s83
	v_add_f32_e32 v49, 1.0, v49
	v_min_f32_e32 v39, 0, v39
	v_cndmask_b32_e64 v48, v50, v48, s[26:27]
	v_cndmask_b32_e64 v50, 0, v241, s[24:25]
	v_cmp_gt_f32_e64 s[24:25], s68, v49
	v_sub_f32_e32 v48, v48, v50
	v_sub_f32_e32 v38, v38, v48
	v_cndmask_b32_e64 v50, 0, 32, s[24:25]
	v_ldexp_f32 v49, v49, v50
	v_log_f32_e32 v49, v49
	v_mul_f32_e64 v50, |v40|, s33
	v_exp_f32_e32 v50, v50
	v_add_f32_e32 v41, v104, v41
	v_mul_f32_e32 v48, 0x3f317217, v49
	v_fma_f32 v48, v49, s2, -v48
	v_fmac_f32_e32 v48, 0x3377d1cf, v49
	v_fmac_f32_e32 v48, 0x3f317217, v49
	v_cmp_lt_f32_e64 s[26:27], |v49|, s83
	v_min_f32_e32 v40, 0, v40
	v_mul_f32_e32 v38, 0x3d800000, v38
	v_cndmask_b32_e64 v48, v49, v48, s[26:27]
	v_cndmask_b32_e64 v49, 0, v241, s[24:25]
	v_sub_f32_e32 v48, v48, v49
; #define LAS __attribute__((address_space(3)))
; __device__ __forceinline__ unsigned pk_bf16(float lo, float hi) { unsigned r; asm volatile("v_cvt_pk_bf16_f32 %0, %1, %2" : "=v"(r) : "v"(lo), "v"(hi)); return r; }
; __device__ __forceinline__ f32x4 mfma16(bf16x8 a, bf16x8 b, f32x4 c) { return __builtin_amdgcn_mfma_f32_16x16x32_bf16(a, b, c, 0, 0, 0); }
; __device__ __forceinline__ void gla_prep(const PrepRegs& R, LAS unsigned char* lds, int wave, int fr, int fq) {
;     ...
;     for (int q = 0; q < 3; ++q) { const int tile = wave * 3 + q, mi = tile / 6, ni = tile % 6, dir = ni / 3, c = (ni % 3) * 16 + fr;
;         const f32x4 acc = mfma16(as_bf8(R.ga[q]), as_bf8(R.bw[q]), (f32x4){0.f, 0.f, 0.f, 0.f});
;         float g[4];
; #pragma unroll
;         for (int i = 0; i < 4; ++i) { const float sv = acc[i] + R.bias[q]; g[i] = (fminf(sv, 0.f) - __logf(1.f + __expf(-fabsf(sv)))) * (1.0f / 16.0f); }
;         u32x2 w2; w2.x = pk_bf16(g[0], g[1]); w2.y = pk_bf16(g[2], g[3]);
;         *(LAS u32x2*)(lds + GL_GT + (dir * 48 + c) * 144 + (mi * 16 + fq * 4) * 2) = w2; }
;     __syncthreads();
; #pragma unroll
;     for (int q = 0; q < 3; ++q) { const int tile = wave * 3 + q, mi = tile / 6, ni = tile % 6, dir = ni / 3;
;         f32x4 acc = (f32x4){0.f, 0.f, 0.f, 0.f};
; #pragma unroll
;         for (int kk = 0; kk < 2; ++kk) { const int t = mi * 16 + fr; bf16x8 tri;
; #pragma unroll
;             for (int e = 0; e < 8; ++e) { const int sidx = kk * 32 + fq * 8 + e; tri[e] = (dir ? (sidx >= t) : (sidx <= t)) ? (short)0x3F80 : (short)0; }
;             const bf16x8 bb = *(const LAS bf16x8*)(lds + GL_GT + (ni * 16 + fr) * 144 + kk * 64 + fq * 16);
;             acc = mfma16(tri, bb, acc); }
	v_add_f32_e32 v49, 1.0, v50
	v_cmp_gt_f32_e64 s[24:25], s68, v49
	v_sub_f32_e32 v39, v39, v48
	v_mul_f32_e32 v39, 0x3d800000, v39
	v_cndmask_b32_e64 v50, 0, 32, s[24:25]
	v_ldexp_f32 v49, v49, v50
	v_log_f32_e32 v49, v49
	v_mul_f32_e64 v50, |v41|, s33
	v_exp_f32_e32 v50, v50
	v_min_f32_e32 v41, 0, v41
	v_mul_f32_e32 v48, 0x3f317217, v49
	v_fma_f32 v48, v49, s2, -v48
	v_fmac_f32_e32 v48, 0x3377d1cf, v49
	v_fmac_f32_e32 v48, 0x3f317217, v49
	v_cmp_lt_f32_e64 s[26:27], |v49|, s83
	v_or_b32_e32 v59, 3, v84
	v_or_b32_e32 v61, 4, v84
	v_cndmask_b32_e64 v48, v49, v48, s[26:27]
	v_cndmask_b32_e64 v49, 0, v241, s[24:25]
	v_sub_f32_e32 v48, v48, v49
	v_add_f32_e32 v49, 1.0, v50
	v_cmp_gt_f32_e64 s[24:25], s68, v49
	v_sub_f32_e32 v40, v40, v48
	v_mul_f32_e32 v40, 0x3d800000, v40
	v_cndmask_b32_e64 v50, 0, 32, s[24:25]
	v_ldexp_f32 v49, v49, v50
	v_log_f32_e32 v49, v49
	v_mad_i32_i24 v50, v89, 48, v76
	v_or_b32_e32 v74, 5, v84
	v_or_b32_e32 v76, 6, v84
	v_mul_f32_e32 v48, 0x3f317217, v49
	v_fma_f32 v48, v49, s2, -v48
	v_fmac_f32_e32 v48, 0x3377d1cf, v49
	v_fmac_f32_e32 v48, 0x3f317217, v49
	v_cmp_lt_f32_e64 s[26:27], |v49|, s83
	v_or_b32_e32 v100, 34, v84
	v_or_b32_e32 v103, 36, v84
	v_cndmask_b32_e64 v48, v49, v48, s[26:27]
	v_cndmask_b32_e64 v49, 0, v241, s[24:25]
	v_sub_f32_e32 v48, v48, v49
	v_sub_f32_e32 v41, v41, v48
	v_mul_f32_e32 v41, 0x3d800000, v41
	v_cvt_pk_bf16_f32 v48, v38, v39
	v_cvt_pk_bf16_f32 v49, v40, v41
	s_waitcnt vmcnt(3)
	v_mfma_f32_16x16x32_bf16 v[38:41], v[42:45], v[54:57], 0
	v_mul_lo_u32 v43, v50, s55
	v_add_u32_e32 v43, 0, v43
	v_lshlrev_b32_e32 v44, 5, v101
	v_add3_u32 v43, v43, v44, v84
	ds_write_b64 v43, v[48:49]
	s_waitcnt vmcnt(2)
	s_nop 1
	v_add_f32_e32 v38, v105, v38
	v_mul_f32_e64 v42, |v38|, s33
	v_exp_f32_e32 v42, v42
	v_add_f32_e32 v39, v105, v39
	v_mul_f32_e64 v44, |v39|, s33
	v_exp_f32_e32 v44, v44
	v_add_f32_e32 v42, 1.0, v42
	v_cmp_gt_f32_e64 s[24:25], s68, v42
	v_min_f32_e32 v38, 0, v38
	v_add_f32_e32 v40, v105, v40
	v_cndmask_b32_e64 v45, 0, 32, s[24:25]
	v_ldexp_f32 v42, v42, v45
	v_log_f32_e32 v42, v42
	v_min_f32_e32 v39, 0, v39
	v_add_f32_e32 v41, v105, v41
	v_or_b32_e32 v56, 1, v84
	v_mul_f32_e32 v43, 0x3f317217, v42
	v_fma_f32 v43, v42, s2, -v43
	v_fmac_f32_e32 v43, 0x3377d1cf, v42
	v_fmac_f32_e32 v43, 0x3f317217, v42
	v_cmp_lt_f32_e64 s[26:27], |v42|, s83
	v_or_b32_e32 v57, 2, v84
	v_or_b32_e32 v101, 35, v84
	v_cndmask_b32_e64 v42, v42, v43, s[26:27]
	v_cndmask_b32_e64 v43, 0, v241, s[24:25]
	v_sub_f32_e32 v42, v42, v43
	v_add_f32_e32 v43, 1.0, v44
	v_cmp_gt_f32_e64 s[24:25], s68, v43
	v_sub_f32_e32 v38, v38, v42
	v_mul_f32_e32 v38, 0x3d800000, v38
	v_cndmask_b32_e64 v44, 0, 32, s[24:25]
	v_ldexp_f32 v43, v43, v44
	v_log_f32_e32 v43, v43
	v_mul_f32_e64 v44, |v40|, s33
	v_exp_f32_e32 v44, v44
	v_min_f32_e32 v40, 0, v40
	v_mul_f32_e32 v42, 0x3f317217, v43
	v_fma_f32 v42, v43, s2, -v42
	v_fmac_f32_e32 v42, 0x3377d1cf, v43
	v_fmac_f32_e32 v42, 0x3f317217, v43
	v_cmp_lt_f32_e64 s[26:27], |v43|, s83
	v_or_b32_e32 v104, 37, v84
	v_or_b32_e32 v106, 38, v84
	v_cndmask_b32_e64 v42, v43, v42, s[26:27]
	v_cndmask_b32_e64 v43, 0, v241, s[24:25]
	v_sub_f32_e32 v42, v42, v43
	v_add_f32_e32 v43, 1.0, v44
	v_cmp_gt_f32_e64 s[24:25], s68, v43
	v_sub_f32_e32 v39, v39, v42
	v_mul_f32_e32 v39, 0x3d800000, v39
	v_cndmask_b32_e64 v44, 0, 32, s[24:25]
	v_ldexp_f32 v43, v43, v44
	v_log_f32_e32 v43, v43
	v_mul_f32_e64 v44, |v41|, s33
	v_exp_f32_e32 v44, v44
	v_min_f32_e32 v41, 0, v41
	v_mul_f32_e32 v42, 0x3f317217, v43
	v_fma_f32 v42, v43, s2, -v42
	v_fmac_f32_e32 v42, 0x3377d1cf, v43
	v_fmac_f32_e32 v42, 0x3f317217, v43
	v_cmp_lt_f32_e64 s[26:27], |v43|, s83
	v_cvt_pk_bf16_f32 v38, v38, v39
	s_nop 1
	v_cndmask_b32_e64 v42, v43, v42, s[26:27]
	v_cndmask_b32_e64 v43, 0, v241, s[24:25]
	v_sub_f32_e32 v42, v42, v43
	v_add_f32_e32 v43, 1.0, v44
	v_cmp_gt_f32_e64 s[24:25], s68, v43
	v_sub_f32_e32 v40, v40, v42
	v_mul_f32_e32 v40, 0x3d800000, v40
	v_cndmask_b32_e64 v44, 0, 32, s[24:25]
	v_ldexp_f32 v43, v43, v44
	v_log_f32_e32 v43, v43
	s_nop 0
	v_mul_f32_e32 v42, 0x3f317217, v43
	v_fma_f32 v42, v43, s2, -v42
	v_fmac_f32_e32 v42, 0x3377d1cf, v43
	v_fmac_f32_e32 v42, 0x3f317217, v43
	v_cmp_lt_f32_e64 s[26:27], |v43|, s83
	s_nop 1
	v_cndmask_b32_e64 v42, v43, v42, s[26:27]
	v_cndmask_b32_e64 v43, 0, v241, s[24:25]
	v_sub_f32_e32 v42, v42, v43
	v_sub_f32_e32 v41, v41, v42
	v_mul_f32_e32 v41, 0x3d800000, v41
	v_cvt_pk_bf16_f32 v39, v40, v41
	v_mad_i32_i24 v40, v77, 48, v78
	v_mul_lo_u32 v40, v40, s55
	v_add_u32_e32 v40, 0, v40
	v_lshlrev_b32_e32 v41, 5, v102
	v_add3_u32 v40, v40, v41, v84
	ds_write_b64 v40, v[38:39]
	v_or_b32_e32 v39, v93, v81
	v_add_u32_e32 v38, 0, v0
	v_lshl_or_b32 v41, v99, 4, v81
	v_cmp_le_i32_e64 s[24:25], v84, v39
	v_add_u32_e32 v40, 2, v99
	v_mad_i32_i24 v44, v41, s55, v38
	v_cndmask_b32_e64 v41, 0, 1, s[24:25]
	v_cmp_ge_i32_e64 s[24:25], v84, v39
	v_or_b32_e32 v78, 7, v84
	s_waitcnt lgkmcnt(0)
	v_cndmask_b32_e64 v42, 0, 1, s[24:25]
	v_cmp_gt_u32_e64 s[24:25], 5, v40
	s_barrier
	s_lshr_b32 s100, s89, 7
	s_lshl_b32 s100, s100, 4
	v_add_u32_e32 v160, s100, v81
	v_sub_u32_e32 v160, v160, v84
	v_subrev_u32_e32 v161, 32, v160
	v_lshlrev_b32_e32 v160, 4, v160
	v_lshlrev_b32_e32 v161, 4, v161
	v_mov_b32_e32 v166, 0x3f803f80
	v_mov_b32_e32 v167, 0
	s_bitcmp1_b32 s89, 6
	s_cbranch_scc1 .Ltri_dir1_g3
	v_sub_u32_e32 v162, 16, v160
	v_med3_i32 v162, v162, 0, 32
	v_lshrrev_b64 v[164:165], v162, v[166:167]
	v_mov_b32_e32 v152, v164
	v_sub_u32_e32 v162, 48, v160
	v_med3_i32 v162, v162, 0, 32
	v_lshrrev_b64 v[164:165], v162, v[166:167]
	v_mov_b32_e32 v153, v164
	v_sub_u32_e32 v162, 0x50, v160
	v_med3_i32 v162, v162, 0, 32
	v_lshrrev_b64 v[164:165], v162, v[166:167]
	v_mov_b32_e32 v154, v164
	v_sub_u32_e32 v162, 0x70, v160
	v_med3_i32 v162, v162, 0, 32
	v_lshrrev_b64 v[164:165], v162, v[166:167]
	v_mov_b32_e32 v155, v164
	v_sub_u32_e32 v162, 16, v161
	v_med3_i32 v162, v162, 0, 32
	v_lshrrev_b64 v[164:165], v162, v[166:167]
	v_mov_b32_e32 v156, v164
	v_sub_u32_e32 v162, 48, v161
	v_med3_i32 v162, v162, 0, 32
	v_lshrrev_b64 v[164:165], v162, v[166:167]
	v_mov_b32_e32 v157, v164
	v_sub_u32_e32 v162, 0x50, v161
	v_med3_i32 v162, v162, 0, 32
	v_lshrrev_b64 v[164:165], v162, v[166:167]
	v_mov_b32_e32 v158, v164
	v_sub_u32_e32 v162, 0x70, v161
	v_med3_i32 v162, v162, 0, 32
	v_lshrrev_b64 v[164:165], v162, v[166:167]
	v_mov_b32_e32 v159, v164
	s_branch .Ltri_done_g3

; #define LAS __attribute__((address_space(3)))
; __device__ __forceinline__ f32x4 mfma16(bf16x8 a, bf16x8 b, f32x4 c) { return __builtin_amdgcn_mfma_f32_16x16x32_bf16(a, b, c, 0, 0, 0); }
; __device__ __forceinline__ void gla_prep(const PrepRegs& R, LAS unsigned char* lds, int wave, int fr, int fq) {
;     ...
; #pragma unroll
;     for (int q = 0; q < 3; ++q) { const int tile = wave * 3 + q, mi = tile / 6, ni = tile % 6, dir = ni / 3;
;         f32x4 acc = (f32x4){0.f, 0.f, 0.f, 0.f};
; #pragma unroll
;         for (int kk = 0; kk < 2; ++kk) { const int t = mi * 16 + fr; bf16x8 tri;
; #pragma unroll
;             for (int e = 0; e < 8; ++e) { const int sidx = kk * 32 + fq * 8 + e; tri[e] = (dir ? (sidx >= t) : (sidx <= t)) ? (short)0x3F80 : (short)0; }
;             const bf16x8 bb = *(const LAS bf16x8*)(lds + GL_GT + (ni * 16 + fr) * 144 + kk * 64 + fq * 16);
;             acc = mfma16(tri, bb, acc); }
; #pragma unroll
;         for (int i = 0; i < 4; ++i) G[(dir * 64 + mi * 16 + fq * 4 + i) * 48 + (ni % 3) * 16 + fr] = acc[i]; }
;     __syncthreads();
.Ltri_done_g3:
	s_nop 0
	v_or_b32_e32 v99, 33, v84
	ds_read_b128 v[48:51], v44
	ds_read_b128 v[52:55], v44 offset:64
	s_waitcnt lgkmcnt(1)
	v_mfma_f32_16x16x32_bf16 v[42:45], v[152:155], v[48:51], 0
	v_or_b32_e32 v41, 32, v84
	v_lshlrev_b32_e32 v40, 2, v96
	v_or_b32_e32 v107, 39, v84
	v_lshl_add_u32 v39, v81, 2, 0
	s_waitcnt lgkmcnt(0)
	v_mfma_f32_16x16x32_bf16 v[42:45], v[156:159], v[52:55], v[42:45]
	v_lshl_add_u32 v48, v94, 6, v93
	v_or_b32_e32 v48, v48, v40
	v_lshlrev_b32_e32 v49, 6, v95
	v_mul_lo_u32 v48, v48, s69
	v_add3_u32 v48, v39, v49, v48
	v_add_u32_e32 v49, 0x3400, v48
	v_or_b32_e32 v93, v88, v81
	s_nop 7
	ds_write2_b32 v49, v42, v43 offset0:128 offset1:176
	v_add_u32_e32 v42, 0x3600, v48
	v_lshl_or_b32 v43, v98, 4, v81
	ds_write2_b32 v42, v44, v45 offset0:96 offset1:144
	v_add_u32_e32 v42, 2, v98
	v_mad_u64_u32 v[52:53], s[4:5], v43, s55, v[38:39]
	v_cmp_gt_u32_e64 s[24:25], 5, v42
	ds_read_b128 v[48:51], v52
	ds_read_b128 v[52:55], v52 offset:64
	s_waitcnt lgkmcnt(1)
	v_mfma_f32_16x16x32_bf16 v[42:45], v[152:155], v[48:51], 0
	s_waitcnt lgkmcnt(0)
	v_mfma_f32_16x16x32_bf16 v[42:45], v[156:159], v[52:55], v[42:45]
	v_lshl_add_u32 v48, v89, 6, v88
	v_or_b32_e32 v48, v48, v40
	v_lshlrev_b32_e32 v49, 6, v91
	v_mul_lo_u32 v48, v48, s69
	v_add3_u32 v48, v39, v49, v48
	v_add_u32_e32 v49, 0x3400, v48
	v_or_b32_e32 v88, v75, v81
	s_nop 7
	ds_write2_b32 v49, v42, v43 offset0:128 offset1:176
	v_add_u32_e32 v42, 0x3600, v48
	v_lshl_or_b32 v43, v97, 4, v81
	ds_write2_b32 v42, v44, v45 offset0:96 offset1:144
	v_add_u32_e32 v42, 2, v97
	v_mad_u64_u32 v[52:53], s[4:5], v43, s55, v[38:39]
	v_cmp_gt_u32_e64 s[24:25], 5, v42
	ds_read_b128 v[48:51], v52
	ds_read_b128 v[52:55], v52 offset:64
	s_waitcnt lgkmcnt(1)
	v_mfma_f32_16x16x32_bf16 v[42:45], v[152:155], v[48:51], 0
	v_lshl_add_u32 v41, v77, 6, v75
	v_or_b32_e32 v41, v41, v40
	v_mul_lo_u32 v41, v41, s69
	s_waitcnt lgkmcnt(0)
	v_mfma_f32_16x16x32_bf16 v[42:45], v[156:159], v[52:55], v[42:45]
	v_lshlrev_b32_e32 v48, 6, v85
	v_add3_u32 v41, v39, v48, v41
	v_add_u32_e32 v48, 0x3400, v41
	v_add_u32_e32 v41, 0x3600, v41
	s_nop 7
	ds_write2_b32 v48, v42, v43 offset0:128 offset1:176
	ds_write2_b32 v41, v44, v45 offset0:96 offset1:144
	s_waitcnt lgkmcnt(0)
	s_barrier
	s_and_saveexec_b64 s[24:25], s[22:23]
	s_cbranch_execz .LBB0_993
; #define LAS __attribute__((address_space(3)))
; __device__ __forceinline__ unsigned pk_bf16(float lo, float hi) { unsigned r; asm volatile("v_cvt_pk_bf16_f32 %0, %1, %2" : "=v"(r) : "v"(lo), "v"(hi)); return r; }
; __device__ __forceinline__ float bflo(unsigned w) { return __uint_as_float(w << 16); }
; __device__ __forceinline__ void gla_g3_item(int wv, const Params& p, int l, int b, int n, int h, LAS unsigned char* lds) {
;     ...
;     if (tid < 384) { const int t = t3;
;         float q1[4] = {bflo(q1w.x), bfhi(q1w.x), bflo(q1w.y), bfhi(q1w.y)}, q2[4] = {bflo(q2w.x), bfhi(q2w.x), bflo(q2w.y), bfhi(q2w.y)};
;         float k1[4] = {bflo(k1w.x), bfhi(k1w.x), bflo(k1w.y), bfhi(k1w.y)}, k2[4] = {bflo(k2w.x), bfhi(k2w.x), bflo(k2w.y), bfhi(k2w.y)};
;         { const float cn[4] = {ra[0], ra[2], rb[0], rb[2]}, sn[4] = {ra[1], ra[3], rb[1], rb[3]};
; #pragma unroll
;             for (int e = 0; e < 4; ++e) { float a1 = q1[e], a2 = q2[e]; q1[e] = a1 * cn[e] - a2 * sn[e]; q2[e] = a2 * cn[e] + a1 * sn[e];
;                 a1 = k1[e]; a2 = k2[e]; k1[e] = a1 * cn[e] - a2 * sn[e]; k2[e] = a2 * cn[e] + a1 * sn[e]; } }
; #pragma unroll
;         for (int dir = 0; dir < 2; ++dir) {
;             const f32x4 b1 = *(const LAS f32x4*)(G + (dir * 64 + t) * 48 + c1), b2 = *(const LAS f32x4*)(G + (dir * 64 + t) * 48 + c1 + 12);
;             float e1[4], e2[4], i1[4], i2[4];
; #pragma unroll
;             for (int e = 0; e < 4; ++e) { e1[e] = __expf(b1[e]); e2[e] = __expf(b2[e]); i1[e] = __expf(-b1[e]); i2[e] = __expf(-b2[e]); }
;             const float qs = 0.14433756729740643f;
;             u32x2 w;
;             w.x = pk_bf16(q1[0] * qs * e1[0], q1[1] * qs * e1[1]); w.y = pk_bf16(q1[2] * qs * e1[2], q1[3] * qs * e1[3]); *(LAS u32x2*)(lds + GL_Q + (dir * 64 + t) * 144 + c1 * 2) = w;
;             w.x = pk_bf16(q2[0] * qs * e2[0], q2[1] * qs * e2[1]); w.y = pk_bf16(q2[2] * qs * e2[2], q2[3] * qs * e2[3]); *(LAS u32x2*)(lds + GL_Q + (dir * 64 + t) * 144 + (c1 + 12) * 2) = w;
;             w.x = pk_bf16(k1[0] * i1[0], k1[1] * i1[1]); w.y = pk_bf16(k1[2] * i1[2], k1[3] * i1[3]); *(LAS u32x2*)(lds + GL_K + (dir * 64 + t) * 144 + c1 * 2) = w;
;             w.x = pk_bf16(k2[0] * i2[0], k2[1] * i2[1]); w.y = pk_bf16(k2[2] * i2[2], k2[3] * i2[3]); *(LAS u32x2*)(lds + GL_K + (dir * 64 + t) * 144 + (c1 + 12) * 2) = w; } }
	v_lshlrev_b32_e32 v43, 16, v72
	v_lshlrev_b32_e32 v42, 16, v70
	v_pk_mul_f32 v[44:45], v[34:35], v[42:43]
	v_pk_mul_f32 v[42:43], v[34:35], v[42:43] op_sel:[0,1] op_sel_hi:[1,0]
	v_sub_f32_e32 v41, v44, v45
	v_add_f32_e32 v48, v42, v43
	v_lshlrev_b32_e32 v43, 16, v68
	v_lshlrev_b32_e32 v42, 16, v66
	v_pk_mul_f32 v[44:45], v[34:35], v[42:43]
	v_pk_mul_f32 v[34:35], v[34:35], v[42:43] op_sel:[0,1] op_sel_hi:[1,0]
	v_sub_f32_e32 v44, v44, v45
	v_add_f32_e32 v45, v34, v35
	v_and_b32_e32 v35, 0xffff0000, v72
	v_and_b32_e32 v34, 0xffff0000, v70
	v_pk_mul_f32 v[42:43], v[36:37], v[34:35]
	v_pk_mul_f32 v[34:35], v[36:37], v[34:35] op_sel:[0,1] op_sel_hi:[1,0]
	v_sub_f32_e32 v49, v42, v43
	v_add_f32_e32 v50, v34, v35
	v_and_b32_e32 v35, 0xffff0000, v68
	v_and_b32_e32 v34, 0xffff0000, v66
	v_pk_mul_f32 v[42:43], v[36:37], v[34:35]
	v_pk_mul_f32 v[34:35], v[36:37], v[34:35] op_sel:[0,1] op_sel_hi:[1,0]
	v_sub_f32_e32 v42, v42, v43
	v_add_f32_e32 v43, v34, v35
	v_lshlrev_b32_e32 v35, 16, v73
	v_lshlrev_b32_e32 v34, 16, v71
	v_pk_mul_f32 v[36:37], v[30:31], v[34:35]
	v_pk_mul_f32 v[34:35], v[30:31], v[34:35] op_sel:[0,1] op_sel_hi:[1,0]
	v_sub_f32_e32 v51, v36, v37
	v_add_f32_e32 v52, v34, v35
	v_lshlrev_b32_e32 v35, 16, v69
	v_lshlrev_b32_e32 v34, 16, v67
	v_pk_mul_f32 v[36:37], v[30:31], v[34:35]
	v_pk_mul_f32 v[30:31], v[30:31], v[34:35] op_sel:[0,1] op_sel_hi:[1,0]
	v_sub_f32_e32 v53, v36, v37
	v_add_f32_e32 v54, v30, v31
	v_and_b32_e32 v31, 0xffff0000, v73
	v_and_b32_e32 v30, 0xffff0000, v71
	v_pk_mul_f32 v[34:35], v[32:33], v[30:31]
	v_pk_mul_f32 v[30:31], v[32:33], v[30:31] op_sel:[0,1] op_sel_hi:[1,0]
	v_sub_f32_e32 v36, v34, v35
	v_add_f32_e32 v55, v30, v31
	v_and_b32_e32 v31, 0xffff0000, v69
	v_and_b32_e32 v30, 0xffff0000, v67
	v_pk_mul_f32 v[34:35], v[32:33], v[30:31]
	v_pk_mul_f32 v[30:31], v[32:33], v[30:31] op_sel:[0,1] op_sel_hi:[1,0]
	v_lshlrev_b32_e32 v61, 1, v64
	v_add_f32_e32 v57, v30, v31
	v_lshlrev_b32_e32 v30, 2, v64
	v_mul_lo_u32 v31, v5, s69
	v_add3_u32 v64, 0, v30, v31
	ds_read_b128 v[30:33], v64 offset:13824
	v_sub_f32_e32 v56, v34, v35
	v_mul_f32_e32 v59, 0x3e13cd3a, v36
	ds_read_b128 v[34:37], v64 offset:13872
	v_mul_f32_e32 v41, 0x3e13cd3a, v41
	s_waitcnt lgkmcnt(1)
	v_mul_f32_e32 v66, 0x3fb8aa3b, v30
	v_mul_f32_e32 v30, 0xbfb8aa3b, v30
	v_exp_f32_e32 v68, v30
	s_waitcnt lgkmcnt(0)
	v_mul_f32_e32 v30, 0xbfb8aa3b, v34
	v_mul_f32_e32 v67, 0x3fb8aa3b, v34
	v_exp_f32_e32 v34, v30
	v_mul_f32_e32 v30, 0x3fb8aa3b, v31
	v_mul_f32_e32 v31, 0xbfb8aa3b, v31
	v_exp_f32_e32 v70, v31
	v_mul_f32_e32 v31, 0xbfb8aa3b, v35
	v_mul_f32_e32 v69, 0x3fb8aa3b, v35
	v_exp_f32_e32 v35, v31
	v_mul_f32_e32 v31, 0x3fb8aa3b, v32
	v_exp_f32_e32 v66, v66
	v_exp_f32_e32 v30, v30
	v_exp_f32_e32 v31, v31
	v_mul_f32_e32 v72, 0x3fb8aa3b, v33
	v_exp_f32_e32 v72, v72
	v_exp_f32_e32 v67, v67
	v_exp_f32_e32 v69, v69
	v_mul_f32_e32 v71, 0x3fb8aa3b, v36
	v_mul_f32_e32 v49, 0x3e13cd3a, v49
	v_mul_f32_e32 v51, 0x3e13cd3a, v51
	v_exp_f32_e32 v71, v71
	v_mul_f32_e32 v73, 0x3fb8aa3b, v37
	v_exp_f32_e32 v73, v73
	v_mul_f32_e32 v66, v41, v66
	v_mul_f32_e32 v30, v49, v30
	v_mul_f32_e32 v31, v51, v31
	v_mul_lo_u32 v5, v5, s55
	v_mul_f32_e32 v48, 0x3e13cd3a, v48
	v_mul_f32_e32 v50, 0x3e13cd3a, v50
	v_mul_f32_e32 v32, 0xbfb8aa3b, v32
	v_cvt_pk_bf16_f32 v30, v66, v30
	v_mul_f32_e32 v66, v59, v72
	v_cvt_pk_bf16_f32 v31, v31, v66
	v_add3_u32 v5, 0, v5, v61
	v_mul_f32_e32 v52, 0x3e13cd3a, v52
	v_exp_f32_e32 v32, v32
	v_mul_f32_e32 v33, 0xbfb8aa3b, v33
	ds_write_b64 v5, v[30:31] offset:39424
	v_mul_f32_e32 v30, v48, v67
	v_mul_f32_e32 v31, v50, v69
	v_mul_f32_e32 v55, 0x3e13cd3a, v55
	v_exp_f32_e32 v33, v33
	v_cvt_pk_bf16_f32 v30, v30, v31
	v_mul_f32_e32 v31, v52, v71
	v_mul_f32_e32 v36, 0xbfb8aa3b, v36
	v_mul_f32_e32 v61, v55, v73
	v_cvt_pk_bf16_f32 v31, v31, v61
	v_exp_f32_e32 v36, v36
	v_mul_f32_e32 v37, 0xbfb8aa3b, v37
	ds_write_b64 v5, v[30:31] offset:39448
	v_mul_f32_e32 v30, v44, v68
	v_mul_f32_e32 v31, v42, v70
	v_exp_f32_e32 v37, v37
	v_cvt_pk_bf16_f32 v30, v30, v31
	v_mul_f32_e32 v31, v53, v32
	v_mul_f32_e32 v32, v56, v33
	v_cvt_pk_bf16_f32 v31, v31, v32
	ds_write_b64 v5, v[30:31] offset:57856
	v_mul_f32_e32 v30, v45, v34
	v_mul_f32_e32 v31, v43, v35
	v_cvt_pk_bf16_f32 v30, v30, v31
	v_mul_f32_e32 v31, v54, v36
	v_mul_f32_e32 v32, v57, v37
	v_cvt_pk_bf16_f32 v31, v31, v32
	ds_write_b64 v5, v[30:31] offset:57880
	ds_read_b128 v[30:33], v64 offset:26112
	ds_read_b128 v[34:37], v64 offset:26160
	s_waitcnt lgkmcnt(1)
	v_mul_f32_e32 v61, 0x3fb8aa3b, v30
	v_mul_f32_e32 v30, 0xbfb8aa3b, v30
	v_exp_f32_e32 v66, v30
	s_waitcnt lgkmcnt(0)
	v_mul_f32_e32 v30, 0xbfb8aa3b, v34
	v_mul_f32_e32 v64, 0x3fb8aa3b, v34
	v_exp_f32_e32 v34, v30
	v_mul_f32_e32 v30, 0x3fb8aa3b, v31
	v_mul_f32_e32 v31, 0xbfb8aa3b, v31
	v_exp_f32_e32 v68, v31
	v_mul_f32_e32 v31, 0xbfb8aa3b, v35
	v_mul_f32_e32 v67, 0x3fb8aa3b, v35
	v_exp_f32_e32 v35, v31
	v_mul_f32_e32 v31, 0x3fb8aa3b, v32
	v_exp_f32_e32 v61, v61
	v_exp_f32_e32 v30, v30
	v_exp_f32_e32 v31, v31
	v_mul_f32_e32 v70, 0x3fb8aa3b, v33
	v_exp_f32_e32 v70, v70
	v_exp_f32_e32 v64, v64
	v_exp_f32_e32 v67, v67
	v_mul_f32_e32 v69, 0x3fb8aa3b, v36
	v_exp_f32_e32 v69, v69
	v_mul_f32_e32 v71, 0x3fb8aa3b, v37
	v_exp_f32_e32 v71, v71
	v_mul_f32_e32 v33, 0xbfb8aa3b, v33
	v_mul_f32_e32 v41, v41, v61
	v_mul_f32_e32 v30, v49, v30
	v_mul_f32_e32 v31, v51, v31
	v_mul_f32_e32 v32, 0xbfb8aa3b, v32
	v_exp_f32_e32 v33, v33
	v_cvt_pk_bf16_f32 v30, v41, v30
	v_mul_f32_e32 v41, v59, v70
	v_cvt_pk_bf16_f32 v31, v31, v41
	v_exp_f32_e32 v32, v32
	v_mul_f32_e32 v37, 0xbfb8aa3b, v37
	ds_write_b64 v5, v[30:31] offset:48640
	v_mul_f32_e32 v30, v48, v64
	v_mul_f32_e32 v31, v50, v67
	v_mul_f32_e32 v36, 0xbfb8aa3b, v36
	v_exp_f32_e32 v37, v37
	v_cvt_pk_bf16_f32 v30, v30, v31
	v_mul_f32_e32 v31, v52, v69
	v_exp_f32_e32 v36, v36
	v_mul_f32_e32 v48, v55, v71
	v_cvt_pk_bf16_f32 v31, v31, v48
	v_add_u32_e32 v41, 0x2400, v5
	ds_write_b64 v5, v[30:31] offset:48664
	v_mul_f32_e32 v5, v44, v66
	v_mul_f32_e32 v30, v42, v68
	v_mul_f32_e32 v31, v56, v33
	v_cvt_pk_bf16_f32 v30, v5, v30
	v_mul_f32_e32 v5, v53, v32
	v_cvt_pk_bf16_f32 v31, v5, v31
	ds_write_b64 v41, v[30:31] offset:57856
	v_mul_f32_e32 v5, v45, v34
	v_mul_f32_e32 v30, v43, v35
	v_mul_f32_e32 v31, v57, v37
	v_cvt_pk_bf16_f32 v30, v5, v30
	v_mul_f32_e32 v5, v54, v36
	v_cvt_pk_bf16_f32 v31, v5, v31
	ds_write_b64 v41, v[30:31] offset:57880

; __global__ void __launch_bounds__(512, 2) hybrid_fwd(Params p_unused) {
	.amdhsa_kernel _Z10hybrid_fwd6Params
		.amdhsa_group_segment_fixed_size 0
		.amdhsa_private_segment_fixed_size 0
		.amdhsa_kernarg_size 432
		.amdhsa_user_sgpr_count 2
		.amdhsa_user_sgpr_dispatch_ptr 0
		.amdhsa_user_sgpr_queue_ptr 0
		.amdhsa_user_sgpr_kernarg_segment_ptr 1
		.amdhsa_user_sgpr_dispatch_id 0
		.amdhsa_user_sgpr_kernarg_preload_length 0
		.amdhsa_user_sgpr_kernarg_preload_offset 0
		.amdhsa_user_sgpr_private_segment_size 0
		.amdhsa_uses_dynamic_stack 0
		.amdhsa_enable_private_segment 0
		.amdhsa_system_sgpr_workgroup_id_x 1
		.amdhsa_system_sgpr_workgroup_id_y 0
		.amdhsa_system_sgpr_workgroup_id_z 0
		.amdhsa_system_sgpr_workgroup_info 0
		.amdhsa_system_vgpr_workitem_id 0
		.amdhsa_next_free_vgpr 256
		.amdhsa_next_free_sgpr 102
		.amdhsa_accum_offset 256
		.amdhsa_reserve_vcc 1
		.amdhsa_float_round_mode_32 0
		.amdhsa_float_round_mode_16_64 0
		.amdhsa_float_denorm_mode_32 3
		.amdhsa_float_denorm_mode_16_64 3
		.amdhsa_dx10_clamp 1
		.amdhsa_ieee_mode 1
		.amdhsa_fp16_overflow 0
		.amdhsa_tg_split 0
		.amdhsa_exception_fp_ieee_invalid_op 0
		.amdhsa_exception_fp_denorm_src 0
		.amdhsa_exception_fp_ieee_div_zero 0
		.amdhsa_exception_fp_ieee_overflow 0
		.amdhsa_exception_fp_ieee_underflow 0
		.amdhsa_exception_fp_ieee_inexact 0
		.amdhsa_exception_int_div_zero 0
	.end_amdhsa_kernel

; __global__ void __launch_bounds__(512, 2) hybrid_fwd(Params p_unused) {
amdhsa.kernels:
  - .agpr_count:     0
    .args:
      - .offset:         0
        .size:           176
        .value_kind:     by_value
      - .offset:         176
        .size:           4
        .value_kind:     hidden_block_count_x
      - .offset:         180
        .size:           4
        .value_kind:     hidden_block_count_y
      - .offset:         184
        .size:           4
        .value_kind:     hidden_block_count_z
      - .offset:         188
        .size:           2
        .value_kind:     hidden_group_size_x
      - .offset:         190
        .size:           2
        .value_kind:     hidden_group_size_y
      - .offset:         192
        .size:           2
        .value_kind:     hidden_group_size_z
      - .offset:         194
        .size:           2
        .value_kind:     hidden_remainder_x
      - .offset:         196
        .size:           2
        .value_kind:     hidden_remainder_y
      - .offset:         198
        .size:           2
        .value_kind:     hidden_remainder_z
      - .offset:         216
        .size:           8
        .value_kind:     hidden_global_offset_x
      - .offset:         224
        .size:           8
        .value_kind:     hidden_global_offset_y
      - .offset:         232
        .size:           8
        .value_kind:     hidden_global_offset_z
      - .offset:         240
        .size:           2
        .value_kind:     hidden_grid_dims
      - .offset:         296
        .size:           4
        .value_kind:     hidden_dynamic_lds_size
    .group_segment_fixed_size: 0
    .kernarg_segment_align: 8
    .kernarg_segment_size: 432
    .language:       OpenCL C
    .language_version:
      - 2
      - 0
    .max_flat_workgroup_size: 512
    .name:           _Z10hybrid_fwd6Params
    .private_segment_fixed_size: 0
    .sgpr_count:     108
    .sgpr_spill_count: 160
    .symbol:         _Z10hybrid_fwd6Params.kd
    .uniform_work_group_size: 1
    .uses_dynamic_stack: false
    .vgpr_count:     256
    .vgpr_spill_count: 0
    .wavefront_size: 64
